# k_pe rope loop (A->B chain): both f32 loads and both cos/sin loads issued before the first wait (one round trip per iteration instead of two)
# speedup vs baseline: 1.0162x; 1.0048x over previous
; #define otid() otid_(wid_k)
; DI float bflo(unsigned u) { return __uint_as_float(u << 16); }
; DI u16 f2bf(float a) { return (u16)(pack2(a, 0.f) & 0xffffu); }
; __global__ void __launch_bounds__(NTHR, 2) fwd_kernel(Params p) {
;     ...
;       } else if (c >= 64) {
;         const int tid = otid();
;         const u16* zpe = WSP(u16, OFF_ZPE); const float* costab = WSP(float, OFF_COS); const float* sintab = WSP(float, OFF_SIN); u16* mk = WSP(u16, OFF_MK);
;         for (int idx = (c - 64) * NTHR + tid; idx < T * 32; idx += 112 * NTHR) {
;           const int m = idx >> 5, f = idx & 31; const int b = m >> 12, s = m & 4095;
;           const float x1 = bflo((unsigned)zpe[(size_t)m * 64 + f]), x2 = bflo((unsigned)zpe[(size_t)m * 64 + 32 + f]);
;           const float cs = costab[idx], sn = sintab[idx];
;           const u16 o1 = f2bf(x1 * cs - x2 * sn), o2 = f2bf(x1 * sn + x2 * cs);
; #pragma unroll
;           for (int hh = 0; hh < 4; ++hh) { u16* kp = mk + (((size_t)b * 4 + hh) * SEQ + s) * 192 + 128; kp[f] = o1; kp[32 + f] = o2; }
;         }
.LBB0_1236:
	v_add_u32_e32 v6, 0xe000, v6
	v_ashrrev_i32_e32 v8, 5, v6
	v_ashrrev_i32_e32 v9, 31, v8
	v_and_b32_e32 v10, 0xfff, v8
	v_lshlrev_b64 v[8:9], 7, v[8:9]
	v_lshl_add_u64 v[8:9], v[2:3], 0, v[8:9]
	global_load_ushort v11, v[8:9], off
	s_mov_b32 s9, 0x200000
	global_load_ushort v8, v[8:9], off offset:64
	v_ashrrev_i32_e32 v7, 17, v6
	global_load_dword v13, v[4:5], off
	v_add_co_u32_e32 v16, vcc, s9, v4
	v_lshl_or_b32 v7, v7, 14, v10
	s_nop 1
	v_addc_co_u32_e32 v17, vcc, 0, v5, vcc
	s_mov_b32 s9, 0x13ea0000
	global_load_dword v16, v[16:17], off
	s_waitcnt vmcnt(3)
	v_lshlrev_b32_e32 v11, 16, v11
	s_waitcnt vmcnt(2)
	v_lshlrev_b32_e32 v12, 16, v8
	s_waitcnt vmcnt(0)
	v_mul_f32_e32 v9, v16, v12
	v_fma_f32 v9, v13, v11, -v9
	v_cvt_pk_bf16_f32 v14, v9, s0
	v_mul_f32_e32 v9, v13, v12
	v_fmac_f32_e32 v9, v16, v11
	v_cvt_pk_bf16_f32 v15, v9, s0
	v_mov_b64_e32 v[8:9], s[2:3]
	v_mad_i64_i32 v[8:9], s[10:11], v7, s0, v[8:9]
	v_lshl_add_u64 v[8:9], v[8:9], 0, v[0:1]
	v_add_co_u32_e32 v12, vcc, s9, v8
	s_mov_b64 s[10:11], 0x13ea0100
	s_nop 0
	v_addc_co_u32_e32 v13, vcc, 0, v9, vcc
	s_mov_b32 s9, 0x14020000
	v_lshl_add_u64 v[10:11], v[8:9], 0, s[10:11]
	global_store_short v[12:13], v14, off offset:256
	global_store_short v[10:11], v15, off offset:64
	v_add_co_u32_e32 v12, vcc, s9, v8
	s_mov_b64 s[10:11], 0x14020100
	s_nop 0
	v_addc_co_u32_e32 v13, vcc, 0, v9, vcc
	v_lshl_add_u64 v[10:11], v[8:9], 0, s[10:11]
	global_store_short v[12:13], v14, off offset:256
	global_store_short v[10:11], v15, off offset:64
	s_mov_b64 s[10:11], 0x141a0100
	v_add_co_u32_e32 v12, vcc, 0x141a0000, v8
	v_lshl_add_u64 v[10:11], v[8:9], 0, s[10:11]
	s_nop 0
	v_addc_co_u32_e32 v13, vcc, 0, v9, vcc
	s_mov_b64 s[10:11], 0x14320100
	global_store_short v[12:13], v14, off offset:256
	global_store_short v[10:11], v15, off offset:64
	v_lshl_add_u64 v[10:11], v[8:9], 0, s[10:11]
	v_add_co_u32_e32 v8, vcc, 0x14320000, v8
	s_mov_b32 s9, 0x71fff
	s_nop 0
	v_addc_co_u32_e32 v9, vcc, 0, v9, vcc
	s_mov_b64 s[10:11], 0x38000
	v_cmp_lt_i32_e32 vcc, s9, v6
	v_lshl_add_u64 v[4:5], v[4:5], 0, s[10:11]
	s_or_b64 s[6:7], vcc, s[6:7]
	global_store_short v[8:9], v14, off offset:256
	global_store_short v[10:11], v15, off offset:64
	s_andn2_b64 exec, exec, s[6:7]
	s_cbranch_execnz .LBB0_1236
